# v13
# speedup vs baseline: 1.0186x; 1.0070x over previous
; __device__ __forceinline__ void attn_mfma_phase(int wave_s, const bf16_t* Z, bf16_t* OG, float* LSE, LAS unsigned char* lds) {
;     ...
;     for (int item = bid; item < 3072; item += gdim) {
;         const int sub = item & 31, bgh = item >> 5, h = bgh & 3, g = (bgh >> 2) % 3, b = bgh / 12;
;         const int d = (g == 0) ? 1 : (g == 1) ? 4 : 16, L = SEQ / d, nqt = 32 / d, r = sub / nqt, qt = sub % nqt;
.LBB0_226:
	s_andn2_b64 vcc, exec, s[4:5]
	s_mov_b64 s[14:15], 0
	s_cbranch_vccnz .LBB0_253
	v_readlane_b32 s4, v255, 10
	s_cmp_gt_i32 s4, 0
	s_mov_b64 s[4:5], -1
	s_cbranch_scc0 .LBB0_251
	v_mov_b32_e32 v0, v141
	v_readlane_b32 s35, v254, 11
	s_movk_i32 s5, 0x1000
	v_readlane_b32 s16, v254, 0
	s_nop 3
	s_and_b32 s32, s35, 7
	s_lshr_b32 s35, s35, 3
	s_mul_i32 s32, s32, 0x180
	s_add_i32 s35, s35, s32
	s_add_i32 s32, s32, 0x180
	s_lshr_b32 s31, s16, 3
	s_cmpk_gt_i32 s35, 0xbff
	s_cbranch_scc1 .LBB0_238
; #define LAS __attribute__((address_space(3)))
; __device__ __forceinline__ void attn_mfma_phase(int wave_s, const bf16_t* Z, bf16_t* OG, float* LSE, LAS unsigned char* lds) {
;     OPAQUE_IDS(); const int wave = tid >> 6, lane = tid & 63, fr = lane & 15, fq = lane >> 4, q4 = (lane & 15) >> 2, p4 = lane & 3;
;     LAS unsigned char* kimg = lds; LAS unsigned char* vimg = lds + 65536;
;     for (int item = bid; item < 3072; item += gdim) {
;         const int sub = item & 31, bgh = item >> 5, h = bgh & 3, g = (bgh >> 2) % 3, b = bgh / 12;
;         const int d = (g == 0) ? 1 : (g == 1) ? 4 : 16, L = SEQ / d, nqt = 32 / d, r = sub / nqt, qt = sub % nqt;
;         const int tile_start = 128 * qt - 64;
;         const bf16_t* zb = Z + (size_t)(b * SEQ + r) * N1 + g * 512 + h * 128;
;         for (int u = tid; u < 4096; u += NTHR) { const int rowl = u >> 4, c = u & 15, lk = tile_start + rowl;
;             u32x4 kv = (u32x4){0u, 0u, 0u, 0u}, vv = (u32x4){0u, 0u, 0u, 0u};
;             if (lk >= 0 && lk < L) { const bf16_t* rp = zb + (size_t)lk * d * N1 + c * 8; kv = *(const u32x4*)(rp + 1536); vv = *(const u32x4*)(rp + 3072); }
;             const int o = img_off(rowl, c); *(LAS u32x4*)(kimg + o) = kv; *(LAS u32x4*)(vimg + o) = vv; }
;         const int lq = 128 * qt + 16 * wave + fr; const size_t qrow = (size_t)(b * SEQ + r) + (size_t)lq * d;
;         bf16x8 qf[4];
; #pragma unroll
;         for (int s = 0; s < 4; ++s) qf[s] = *(const bf16x8*)(zb + (size_t)lq * d * N1 + 32 * s + 8 * fq);
;         __syncthreads();
;         f32x4 sc[9];
; #pragma unroll
;         for (int kbi = 0; kbi < 9; ++kbi) { f32x4 a = (f32x4){0.f, 0.f, 0.f, 0.f}; const int krow = 16 * (wave + kbi) + fr;
; #pragma unroll
;             for (int s = 0; s < 4; ++s) { const bf16x8 kf = *(const LAS bf16x8*)(kimg + img_off(krow, 4 * s + fq)); a = __builtin_amdgcn_mfma_f32_16x16x32_bf16(kf, qf[s], a, 0, 0, 0); }
;             sc[kbi] = a; }
;         const int ql = 64 + 16 * wave + fr; float mx = -1e30f;
; #pragma unroll
;         for (int kbi = 0; kbi < 9; ++kbi)
; #pragma unroll
;             for (int e = 0; e < 4; ++e) { const int kl = 16 * (wave + kbi) + 4 * fq + e, lk = tile_start + kl, dd = kl - ql;
;                 const bool ok = dd >= -64 && dd <= 64 && lk >= 0 && lk < L; const float v = ok ? sc[kbi][e] * 0.08838834764831845f : -1e30f; sc[kbi][e] = v; mx = fmaxf(mx, v); }
	v_mbcnt_lo_u32_b32 v0, -1, v0
	v_mbcnt_hi_u32_b32 v1, -1, v0
	v_readlane_b32 s4, v254, 16
	v_and_b32_e32 v3, 63, v1
	s_waitcnt lgkmcnt(0)
	v_bfe_u32 v5, v1, 4, 2
	v_add_u32_e32 v56, s4, v1
	v_cmp_gt_i32_e64 s[4:5], s5, v56
	v_and_b32_e32 v57, 15, v1
	v_bfe_u32 v7, v1, 2, 2
	v_writelane_b32 v255, s4, 11
	v_lshlrev_b32_e32 v2, 2, v1
	v_bfe_u32 v11, v1, 1, 1
	v_and_b32_e32 v12, 12, v1
	v_lshlrev_b32_e32 v1, 3, v1
	v_writelane_b32 v255, s5, 12
	v_and_b32_e32 v1, 8, v1
	s_add_i32 s4, 0, 0x10000
	v_ashrrev_i32_e32 v6, 6, v56
	v_and_b32_e32 v9, 12, v2
	v_add_u32_e32 v1, s4, v1
	v_cmp_gt_u32_e64 s[4:5], 16, v3
	v_lshlrev_b32_e32 v8, 4, v6
	v_lshlrev_b32_e32 v2, 2, v5
	v_lshlrev_b32_e32 v4, 2, v3
	v_writelane_b32 v255, s4, 13
	v_bitop3_b32 v3, v9, v5, v7 bitop3:0x36
	v_or_b32_e32 v58, v8, v57
	v_writelane_b32 v255, s5, 14
	v_lshlrev_b32_e32 v61, 4, v3
	v_or_b32_e32 v3, 4, v5
	v_or_b32_e32 v74, v8, v2
	v_sub_u32_e32 v8, v2, v57
	s_movk_i32 s4, 0x81
	v_bitop3_b32 v3, v9, v3, v7 bitop3:0x36
	v_cmp_gt_u32_e64 s[6:7], s4, v8
	v_or_b32_e32 v75, 1, v74
	v_lshlrev_b32_e32 v63, 4, v3
	v_or_b32_e32 v3, 8, v5
	v_writelane_b32 v255, s6, 15
	v_sub_u32_e32 v8, v75, v58
	v_bitop3_b32 v3, v9, v3, v7 bitop3:0x36
	v_writelane_b32 v255, s7, 16
	v_cmp_gt_u32_e64 s[6:7], s4, v8
	v_or_b32_e32 v76, 2, v74
	v_lshlrev_b32_e32 v64, 4, v3
	v_or_b32_e32 v3, 12, v5
	v_writelane_b32 v255, s6, 17
	v_sub_u32_e32 v8, v76, v58
	v_bitop3_b32 v3, v9, v3, v7 bitop3:0x36
	v_writelane_b32 v255, s7, 18
	v_cmp_gt_u32_e64 s[6:7], s4, v8
	v_or_b32_e32 v77, 3, v74
	v_lshlrev_b32_e32 v65, 4, v3
	v_add_u32_e32 v3, 1, v6
	v_writelane_b32 v255, s6, 19
	v_sub_u32_e32 v8, v77, v58
	v_lshl_add_u32 v10, v57, 8, 0
	v_writelane_b32 v255, s7, 20
	v_cmp_gt_u32_e64 s[6:7], s4, v8
	v_lshl_or_b32 v78, v3, 4, v2
	v_lshl_add_u32 v66, v3, 12, v10
	v_writelane_b32 v255, s6, 21
	v_sub_u32_e32 v3, v78, v58
	v_or_b32_e32 v79, 1, v78
	v_writelane_b32 v255, s7, 22
	v_cmp_gt_u32_e64 s[6:7], s4, v3
	v_sub_u32_e32 v3, v79, v58
	v_or_b32_e32 v80, 2, v78
	v_writelane_b32 v255, s6, 23
	v_add_u32_e32 v9, 2, v6
	v_or_b32_e32 v81, 3, v78
	v_writelane_b32 v255, s7, 24
	v_cmp_gt_u32_e64 s[6:7], s4, v3
	v_sub_u32_e32 v3, v80, v58
	v_cmp_gt_u32_e64 s[22:23], s4, v3
	v_sub_u32_e32 v3, v81, v58
	v_lshl_or_b32 v82, v9, 4, v2
	v_cmp_gt_u32_e64 s[24:25], s4, v3
	v_sub_u32_e32 v3, v82, v58
	v_or_b32_e32 v83, 1, v82
	v_cmp_gt_u32_e64 s[26:27], s4, v3
	v_sub_u32_e32 v3, v83, v58
	v_or_b32_e32 v84, 2, v82
	v_add_u32_e32 v14, 3, v6
	v_cmp_gt_u32_e64 s[28:29], s4, v3
	v_sub_u32_e32 v3, v84, v58
	v_or_b32_e32 v85, 3, v82
	v_cmp_gt_u32_e64 s[12:13], s4, v3
	v_sub_u32_e32 v3, v85, v58
	v_lshl_or_b32 v86, v14, 4, v2
	v_cmp_gt_u32_e64 s[14:15], s4, v3
	v_sub_u32_e32 v3, v86, v58
	v_or_b32_e32 v87, 1, v86
	v_cmp_gt_u32_e64 s[36:37], s4, v3
	v_sub_u32_e32 v3, v87, v58
	v_or_b32_e32 v88, 2, v86
	v_add_u32_e32 v15, 4, v6
	v_cmp_gt_u32_e64 s[38:39], s4, v3
	v_sub_u32_e32 v3, v88, v58
	v_or_b32_e32 v89, 3, v86
	v_cmp_gt_u32_e64 s[40:41], s4, v3
	v_sub_u32_e32 v3, v89, v58
	v_lshl_or_b32 v90, v15, 4, v2
	v_cmp_gt_u32_e64 s[42:43], s4, v3
	v_sub_u32_e32 v3, v90, v58
	v_or_b32_e32 v91, 1, v90
	v_cmp_gt_u32_e64 s[44:45], s4, v3
	v_sub_u32_e32 v3, v91, v58
	v_or_b32_e32 v92, 2, v90
	v_add_u32_e32 v16, 5, v6
	v_cmp_gt_u32_e64 s[46:47], s4, v3
	v_sub_u32_e32 v3, v92, v58
	v_or_b32_e32 v93, 3, v90
	v_cmp_gt_u32_e64 s[48:49], s4, v3
	v_sub_u32_e32 v3, v93, v58
	v_lshl_or_b32 v94, v16, 4, v2
	v_cmp_gt_u32_e64 s[50:51], s4, v3
	v_sub_u32_e32 v3, v94, v58
	v_or_b32_e32 v95, 1, v94
	v_cmp_gt_u32_e64 s[52:53], s4, v3
	v_sub_u32_e32 v3, v95, v58
	v_or_b32_e32 v96, 2, v94
	v_add_u32_e32 v17, 6, v6
	v_cmp_gt_u32_e64 s[54:55], s4, v3
	v_sub_u32_e32 v3, v96, v58
	v_or_b32_e32 v97, 3, v94
	v_cmp_gt_u32_e64 s[56:57], s4, v3
	v_sub_u32_e32 v3, v97, v58
	v_lshl_or_b32 v98, v17, 4, v2
	v_cmp_gt_u32_e64 s[58:59], s4, v3
	v_sub_u32_e32 v3, v98, v58
	v_or_b32_e32 v99, 1, v98
	v_cmp_gt_u32_e64 s[60:61], s4, v3
	v_sub_u32_e32 v3, v99, v58
	v_or_b32_e32 v100, 2, v98
	v_add_u32_e32 v18, 7, v6
	v_cmp_gt_u32_e64 s[62:63], s4, v3
	v_sub_u32_e32 v3, v100, v58
	v_or_b32_e32 v101, 3, v98
	v_cmp_gt_u32_e64 s[64:65], s4, v3
	v_sub_u32_e32 v3, v101, v58
	v_lshl_or_b32 v102, v18, 4, v2
	v_cmp_gt_u32_e64 s[66:67], s4, v3
	v_sub_u32_e32 v3, v102, v58
	v_or_b32_e32 v103, 1, v102
	v_cmp_gt_u32_e64 s[68:69], s4, v3
	v_sub_u32_e32 v3, v103, v58
	v_or_b32_e32 v104, 2, v102
	v_lshl_add_u32 v62, v6, 12, v10
	v_add_u32_e32 v6, 8, v6
	v_cmp_gt_u32_e64 s[70:71], s4, v3
	v_sub_u32_e32 v3, v104, v58
	v_or_b32_e32 v105, 3, v102
	v_cmp_gt_u32_e64 s[72:73], s4, v3
	v_sub_u32_e32 v3, v105, v58
	v_lshl_or_b32 v106, v6, 4, v2
	v_cmp_gt_u32_e64 s[74:75], s4, v3
	v_sub_u32_e32 v3, v106, v58
	v_or_b32_e32 v107, 1, v106
	v_cmp_gt_u32_e64 s[76:77], s4, v3
	v_sub_u32_e32 v3, v107, v58
	v_or_b32_e32 v108, 2, v106
	v_cmp_gt_u32_e64 s[78:79], s4, v3
	v_sub_u32_e32 v3, v108, v58
	v_or_b32_e32 v109, 3, v106
	v_cmp_gt_u32_e64 s[80:81], s4, v3
	v_sub_u32_e32 v3, v109, v58
	v_cmp_gt_u32_e64 s[82:83], s4, v3
	v_bitop3_b32 v3, v5, v11, v12 bitop3:0x36
	v_or_b32_e32 v13, v5, v12
	v_lshlrev_b32_e32 v110, 4, v3
	v_or_b32_e32 v3, v74, v7
	v_lshl_add_u32 v111, v3, 8, v1
	v_bitop3_b32 v3, v11, v13, 2 bitop3:0x36
	v_lshlrev_b32_e32 v113, 4, v3
	v_bitop3_b32 v3, v11, v13, 4 bitop3:0x36
	v_lshlrev_b32_e32 v114, 4, v3
	v_bitop3_b32 v3, v11, v13, 6 bitop3:0x36
	v_lshlrev_b32_e32 v115, 4, v3
	v_bitop3_b32 v3, v11, v13, 8 bitop3:0x36
	v_lshlrev_b32_e32 v116, 4, v3
	v_bitop3_b32 v3, v11, v13, 10 bitop3:0x36
	v_lshlrev_b32_e32 v117, 4, v3
	v_bitop3_b32 v3, v11, v13, 12 bitop3:0x36
	v_lshlrev_b32_e32 v118, 4, v3
	v_bitop3_b32 v3, v11, v13, 14 bitop3:0x36
	v_lshlrev_b32_e32 v119, 4, v3
	v_or_b32_e32 v3, v82, v7
	v_lshl_add_u32 v120, v3, 8, v1
	v_or_b32_e32 v3, v90, v7
	v_lshl_add_u32 v122, v3, 8, v1
	v_or_b32_e32 v3, v98, v7
	v_lshlrev_b32_e32 v0, 3, v5
	v_xor_b32_e32 v59, 64, v4
	v_xor_b32_e32 v60, 0x80, v4
	v_lshlrev_b32_e32 v4, 3, v57
	v_writelane_b32 v255, s6, 25
	v_or_b32_e32 v5, v78, v7
	v_lshl_add_u32 v124, v3, 8, v1
	v_or_b32_e32 v3, v106, v7
	v_lshl_add_u32 v67, v9, 12, v10
	v_lshl_add_u32 v68, v14, 12, v10
	v_lshl_add_u32 v69, v15, 12, v10
	v_lshl_add_u32 v70, v16, 12, v10
	v_lshl_add_u32 v71, v17, 12, v10
	v_lshl_add_u32 v72, v18, 12, v10
	v_lshl_add_u32 v73, v6, 12, v10
	v_writelane_b32 v255, s7, 26
	v_lshl_add_u32 v112, v5, 8, v1
	v_add_u32_e32 v121, 0x3000, v111
	v_add_u32_e32 v123, 0x5000, v111
	v_add_u32_e32 v125, 0x7000, v111
	v_lshl_add_u32 v126, v3, 8, v1
	v_lshlrev_b32_e32 v48, 1, v4
	v_lshlrev_b32_e32 v50, 1, v0
	v_lshlrev_b32_e32 v52, 1, v2
	s_branch .LBB0_231
.LBB0_230:
	s_or_b64 exec, exec, s[4:5]
	s_add_i32 s35, s35, s31
	s_cmp_lt_i32 s35, s32
	s_barrier
	s_cbranch_scc0 .LBB0_238

; #define LAS __attribute__((address_space(3)))
; __device__ __forceinline__ float bflo(unsigned w) { return __uint_as_float(w << 16); }
; __device__ __forceinline__ float bfhi(unsigned w) { return __uint_as_float(w & 0xffff0000u); }
; __device__ __forceinline__ bf16x8 pack8(f32x4 a, f32x4 b) { u32x4 w; w.x = cvt_pk_bf16(a[0], a[1]); w.y = cvt_pk_bf16(a[2], a[3]); w.z = cvt_pk_bf16(b[0], b[1]); w.w = cvt_pk_bf16(b[2], b[3]); return __builtin_bit_cast(bf16x8, w); }
; __device__ __forceinline__ void sg_mfma_phase(int wave_s, const bf16_t* Z, bf16_t* SGO, const float* sgw, const float* sgb, const float* lng, const float* lnb, LAS unsigned char* lds) {
;     ...
;             for (int u = tid; u < 2048; u += NTHR) { const int j = u >> 4, c = u & 15;
;                 const u32x4 raw = *(const u32x4*)(Z + (row0 + j) * N1 + 5632 + g * 128 + c * 8);
;                 const float mu = st[2 * j], rs = st[2 * j + 1];
;                 const f32x4 g0 = *(const f32x4*)(lng + g * 128 + c * 8), g1 = *(const f32x4*)(lng + g * 128 + c * 8 + 4), b0 = *(const f32x4*)(lnb + g * 128 + c * 8), b1 = *(const f32x4*)(lnb + g * 128 + c * 8 + 4);
;                 f32x4 x0 = (f32x4){bflo(raw.x), bfhi(raw.x), bflo(raw.y), bfhi(raw.y)}, x1 = (f32x4){bflo(raw.z), bfhi(raw.z), bflo(raw.w), bfhi(raw.w)};
;                 x0 = (x0 - mu) * rs * g0 + b0; x1 = (x1 - mu) * rs * g1 + b1;
;                 *(LAS bf16x8*)(img + img_off(j, c)) = pack8(x0, x1); }
.LBB0_249:
	v_ashrrev_i32_e32 v116, 4, v94
	v_ashrrev_i32_e32 v117, 31, v116
	v_lshl_add_u64 v[96:97], s[10:11], 0, v[116:117]
	v_mov_b64_e32 v[98:99], s[2:3]
	v_mad_u64_u32 v[98:99], s[24:25], v96, s33, v[98:99]
	v_mad_i32_i24 v99, v97, s33, v99
	s_lshl_b32 s84, s16, 1
	v_lshl_add_u64 v[96:97], v[98:99], 0, s[84:85]
	v_lshl_add_u64 v[96:97], v[96:97], 0, v[140:141]
	s_movk_i32 s17, 0x2000
	v_add_co_u32_e32 v96, vcc, s17, v96
	v_lshl_add_u32 v95, v116, 3, 0
	s_nop 0
	v_addc_co_u32_e32 v97, vcc, 0, v97, vcc
	s_mov_b64 s[20:21], 0x68000
	global_load_dwordx4 v[100:103], v[66:67], off offset:16
	global_load_dwordx4 v[104:107], v[66:67], off
	global_load_dwordx4 v[108:111], v[68:69], off offset:16
	global_load_dwordx4 v[112:115], v[68:69], off
	global_load_dwordx4 v[170:173], v[96:97], off offset:3072
	v_lshl_add_u64 v[238:239], v[96:97], 0, s[20:21]
	global_load_dwordx4 v[174:177], v[238:239], off offset:3072
	v_lshl_add_u64 v[238:239], v[238:239], 0, s[20:21]
	global_load_dwordx4 v[178:181], v[238:239], off offset:3072
	v_lshl_add_u64 v[238:239], v[238:239], 0, s[20:21]
	global_load_dwordx4 v[182:185], v[238:239], off offset:3072
	ds_read_b64 v[186:187], v95 offset:32768
	ds_read_b64 v[188:189], v95 offset:33024
	ds_read_b64 v[190:191], v95 offset:33280
	ds_read_b64 v[192:193], v95 offset:33536
	v_lshlrev_b32_e32 v95, 8, v116
	v_lshlrev_b32_e32 v206, 2, v116
	v_and_b32_e32 v206, 12, v206
	v_bfe_u32 v207, v116, 2, 2
	v_bitop3_b32 v206, v206, v70, v207 bitop3:0x36
	v_lshlrev_b32_e32 v206, 4, v206
	v_add3_u32 v95, 0, v206, v95
	s_waitcnt vmcnt(3)
	s_waitcnt lgkmcnt(0)
	v_lshlrev_b32_e32 v194, 16, v170
	v_and_b32_e32 v195, 0xffff0000, v170
	v_lshlrev_b32_e32 v196, 16, v171
	v_and_b32_e32 v197, 0xffff0000, v171
	v_lshlrev_b32_e32 v198, 16, v172
	v_and_b32_e32 v199, 0xffff0000, v172
	v_lshlrev_b32_e32 v200, 16, v173
	v_and_b32_e32 v201, 0xffff0000, v173
	v_sub_f32_e32 v194, v194, v186
	v_sub_f32_e32 v195, v195, v186
	v_sub_f32_e32 v196, v196, v186
	v_sub_f32_e32 v197, v197, v186
	v_sub_f32_e32 v198, v198, v186
	v_sub_f32_e32 v199, v199, v186
	v_sub_f32_e32 v200, v200, v186
	v_sub_f32_e32 v201, v201, v186
	v_pk_mul_f32 v[194:195], v[186:187], v[194:195] op_sel:[1,0]
	v_pk_mul_f32 v[196:197], v[186:187], v[196:197] op_sel:[1,0]
	v_pk_mul_f32 v[198:199], v[186:187], v[198:199] op_sel:[1,0]
	v_pk_mul_f32 v[200:201], v[186:187], v[200:201] op_sel:[1,0]
	v_pk_fma_f32 v[194:195], v[104:105], v[194:195], v[112:113]
	v_pk_fma_f32 v[196:197], v[106:107], v[196:197], v[114:115]
	v_pk_fma_f32 v[198:199], v[100:101], v[198:199], v[108:109]
	v_pk_fma_f32 v[200:201], v[102:103], v[200:201], v[110:111]
	v_cvt_pk_bf16_f32 v202, v194, v195
	v_cvt_pk_bf16_f32 v203, v196, v197
	v_cvt_pk_bf16_f32 v204, v198, v199
	v_cvt_pk_bf16_f32 v205, v200, v201
	s_nop 0
	ds_write_b128 v95, v[202:205]
	s_waitcnt vmcnt(2)
	v_lshlrev_b32_e32 v194, 16, v174
	v_and_b32_e32 v195, 0xffff0000, v174
	v_lshlrev_b32_e32 v196, 16, v175
	v_and_b32_e32 v197, 0xffff0000, v175
	v_lshlrev_b32_e32 v198, 16, v176
	v_and_b32_e32 v199, 0xffff0000, v176
	v_lshlrev_b32_e32 v200, 16, v177
	v_and_b32_e32 v201, 0xffff0000, v177
	v_sub_f32_e32 v194, v194, v188
	v_sub_f32_e32 v195, v195, v188
	v_sub_f32_e32 v196, v196, v188
	v_sub_f32_e32 v197, v197, v188
	v_sub_f32_e32 v198, v198, v188
	v_sub_f32_e32 v199, v199, v188
	v_sub_f32_e32 v200, v200, v188
	v_sub_f32_e32 v201, v201, v188
	v_pk_mul_f32 v[194:195], v[188:189], v[194:195] op_sel:[1,0]
	v_pk_mul_f32 v[196:197], v[188:189], v[196:197] op_sel:[1,0]
	v_pk_mul_f32 v[198:199], v[188:189], v[198:199] op_sel:[1,0]
	v_pk_mul_f32 v[200:201], v[188:189], v[200:201] op_sel:[1,0]
	v_pk_fma_f32 v[194:195], v[104:105], v[194:195], v[112:113]
	v_pk_fma_f32 v[196:197], v[106:107], v[196:197], v[114:115]
	v_pk_fma_f32 v[198:199], v[100:101], v[198:199], v[108:109]
	v_pk_fma_f32 v[200:201], v[102:103], v[200:201], v[110:111]
	v_cvt_pk_bf16_f32 v202, v194, v195
	v_cvt_pk_bf16_f32 v203, v196, v197
	v_cvt_pk_bf16_f32 v204, v198, v199
	v_cvt_pk_bf16_f32 v205, v200, v201
	s_nop 0
	ds_write_b128 v95, v[202:205] offset:8192
	s_waitcnt vmcnt(1)
	v_lshlrev_b32_e32 v194, 16, v178
	v_and_b32_e32 v195, 0xffff0000, v178
	v_lshlrev_b32_e32 v196, 16, v179
	v_and_b32_e32 v197, 0xffff0000, v179
	v_lshlrev_b32_e32 v198, 16, v180
	v_and_b32_e32 v199, 0xffff0000, v180
	v_lshlrev_b32_e32 v200, 16, v181
	v_and_b32_e32 v201, 0xffff0000, v181
	v_sub_f32_e32 v194, v194, v190
	v_sub_f32_e32 v195, v195, v190
	v_sub_f32_e32 v196, v196, v190
	v_sub_f32_e32 v197, v197, v190
	v_sub_f32_e32 v198, v198, v190
	v_sub_f32_e32 v199, v199, v190
	v_sub_f32_e32 v200, v200, v190
	v_sub_f32_e32 v201, v201, v190
	v_pk_mul_f32 v[194:195], v[190:191], v[194:195] op_sel:[1,0]
	v_pk_mul_f32 v[196:197], v[190:191], v[196:197] op_sel:[1,0]
	v_pk_mul_f32 v[198:199], v[190:191], v[198:199] op_sel:[1,0]
	v_pk_mul_f32 v[200:201], v[190:191], v[200:201] op_sel:[1,0]
	v_pk_fma_f32 v[194:195], v[104:105], v[194:195], v[112:113]
	v_pk_fma_f32 v[196:197], v[106:107], v[196:197], v[114:115]
	v_pk_fma_f32 v[198:199], v[100:101], v[198:199], v[108:109]
	v_pk_fma_f32 v[200:201], v[102:103], v[200:201], v[110:111]
	v_cvt_pk_bf16_f32 v202, v194, v195
	v_cvt_pk_bf16_f32 v203, v196, v197
	v_cvt_pk_bf16_f32 v204, v198, v199
	v_cvt_pk_bf16_f32 v205, v200, v201
	s_nop 0
	ds_write_b128 v95, v[202:205] offset:16384
	s_waitcnt vmcnt(0)
	v_lshlrev_b32_e32 v194, 16, v182
	v_and_b32_e32 v195, 0xffff0000, v182
	v_lshlrev_b32_e32 v196, 16, v183
	v_and_b32_e32 v197, 0xffff0000, v183
	v_lshlrev_b32_e32 v198, 16, v184
	v_and_b32_e32 v199, 0xffff0000, v184
	v_lshlrev_b32_e32 v200, 16, v185
	v_and_b32_e32 v201, 0xffff0000, v185
	v_sub_f32_e32 v194, v194, v192
	v_sub_f32_e32 v195, v195, v192
	v_sub_f32_e32 v196, v196, v192
	v_sub_f32_e32 v197, v197, v192
	v_sub_f32_e32 v198, v198, v192
	v_sub_f32_e32 v199, v199, v192
	v_sub_f32_e32 v200, v200, v192
	v_sub_f32_e32 v201, v201, v192
	v_pk_mul_f32 v[194:195], v[192:193], v[194:195] op_sel:[1,0]
	v_pk_mul_f32 v[196:197], v[192:193], v[196:197] op_sel:[1,0]
	v_pk_mul_f32 v[198:199], v[192:193], v[198:199] op_sel:[1,0]
	v_pk_mul_f32 v[200:201], v[192:193], v[200:201] op_sel:[1,0]
	v_pk_fma_f32 v[194:195], v[104:105], v[194:195], v[112:113]
	v_pk_fma_f32 v[196:197], v[106:107], v[196:197], v[114:115]
	v_pk_fma_f32 v[198:199], v[100:101], v[198:199], v[108:109]
	v_pk_fma_f32 v[200:201], v[102:103], v[200:201], v[110:111]
	v_cvt_pk_bf16_f32 v202, v194, v195
	v_cvt_pk_bf16_f32 v203, v196, v197
	v_cvt_pk_bf16_f32 v204, v198, v199
	v_cvt_pk_bf16_f32 v205, v200, v201
	s_nop 0
	ds_write_b128 v95, v[202:205] offset:24576
	s_branch .LBB0_246
